# NA softmax steps: V fragments for the PV MFMAs prefetched into free registers instead of one LDS round trip per MFMA
# speedup vs baseline: 1.0070x; 1.0008x over previous
; #define LAS __attribute__((address_space(3)))
; __device__ __forceinline__ unsigned pk_bf16(float lo, float hi) { unsigned r; asm volatile("v_cvt_pk_bf16_f32 %0, %1, %2" : "=v"(r) : "v"(lo), "v"(hi)); return r; }
; __device__ __forceinline__ f32x4 mfma16(bf16x8 a, bf16x8 b, f32x4 c) { return __builtin_amdgcn_mfma_f32_16x16x32_bf16(a, b, c, 0, 0, 0); }
; template <int ND> ...
;     f32x4 sc[2 * ND];
; #pragma unroll
;     for (int u = 0; u < 2 * ND; ++u) sc[u] = (f32x4){0.f, 0.f, 0.f, 0.f};
;     __builtin_amdgcn_s_setprio(1);
; #pragma unroll
;     for (int kk = 0; kk < 2; ++kk)
; #pragma unroll
;         for (int u = 0; u < 2 * ND; ++u) {
;             const bf16x8 kf = *(const LAS bf16x8*)(lds + kbase + (key0[u >> 1] + (u & 1) * 16 + fr) * 144 + kk * 64 + fq * 16);
;             sc[u] = mfma16(kf, qf[kk], sc[u]); }
;     __builtin_amdgcn_s_setprio(0);
;     if (loc) {
; #pragma unroll
;         for (int g = 0; g < ND; ++g)
; #pragma unroll
;             for (int i = 0; i < 4; ++i) {
;                 const int ck0 = cst + fq * 4 + i, ck1 = ck0 + 16;
;                 const int rel0 = min(max(ck0 - cq + 15, 0), 30), rel1 = min(max(ck1 - cq + 15, 0), 30);
;                 const bool v0 = (ck0 >= c0w) && (ck0 < c0w + 16), v1 = (ck1 >= c0w) && (ck1 < c0w + 16);
;                 sc[2 * g][i] = v0 ? sc[2 * g][i] + rpb[dr[g] * 31 + rel0] : -INFINITY;
;                 sc[2 * g + 1][i] = v1 ? sc[2 * g + 1][i] + rpb[dr[g] * 31 + rel1] : -INFINITY; }
;     }
;     float mx = -INFINITY;
; #pragma unroll
;     for (int u = 0; u < 2 * ND; ++u) mx = fmaxf(mx, fmaxf(fmaxf(sc[u][0], sc[u][1]), fmaxf(sc[u][2], sc[u][3])));
;     mx = xmax16(mx); mx = xmax32(mx);
;     const float m_new = fmaxf(m_run, mx);
;     const float m_use = (m_new == -INFINITY) ? 0.f : m_new;
;     const float alpha = __builtin_amdgcn_exp2f(m_run - m_use);
;     float ps_sum = 0.f; bf16x8 pf[ND];
; #pragma unroll
;     for (int g = 0; g < ND; ++g) { float pv[8];
; #pragma unroll
;         for (int i = 0; i < 4; ++i) { pv[i] = __builtin_amdgcn_exp2f(sc[2 * g][i] - m_use); pv[4 + i] = __builtin_amdgcn_exp2f(sc[2 * g + 1][i] - m_use); ps_sum += pv[i] + pv[4 + i]; }
;         u32x4 pw; pw.x = pk_bf16(pv[0], pv[1]); pw.y = pk_bf16(pv[2], pv[3]); pw.z = pk_bf16(pv[4], pv[5]); pw.w = pk_bf16(pv[6], pv[7]);
;         pf[g] = as_bf8(pw); }
;     l_run = l_run * alpha + ps_sum; m_run = m_new;
.LBB0_737:
	s_setprio 1
	v_add_u32_e32 v234, v159, v105
	ds_read2_b64 v[220:223], v234 offset1:4
	ds_read2_b64 v[224:227], v187 offset1:4
	v_add_u32_e32 v235, 0x2000, v234
	ds_read2_b64 v[248:251], v235 offset0:64 offset1:68
	ds_read_b128 v[84:87], v186
	ds_read_b128 v[210:213], v186 offset:64
	ds_read_b128 v[88:91], v186 offset:2304
	ds_read_b128 v[92:95], v186 offset:4608
	ds_read_b128 v[96:99], v186 offset:6912
	ds_read_b128 v[188:191], v186 offset:9216
	ds_read_b128 v[198:201], v186 offset:13824
	ds_read_b128 v[214:217], v186 offset:13888
	ds_read_b128 v[192:195], v186 offset:11520
	s_waitcnt lgkmcnt(8)
	v_mfma_f32_16x16x32_bf16 v[84:87], v[84:87], v[4:7], 0
	ds_read_b128 v[206:209], v186 offset:16128
	s_waitcnt lgkmcnt(8)
	v_mfma_f32_16x16x32_bf16 v[84:87], v[210:213], v[8:11], v[84:87]
	ds_read_b128 v[210:213], v186 offset:2368
	s_waitcnt lgkmcnt(8)
	v_mfma_f32_16x16x32_bf16 v[88:91], v[88:91], v[4:7], 0
	s_waitcnt lgkmcnt(4)
	v_mfma_f32_16x16x32_bf16 v[198:201], v[198:201], v[4:7], 0
	s_waitcnt lgkmcnt(0)
	v_mfma_f32_16x16x32_bf16 v[88:91], v[210:213], v[8:11], v[88:91]
	ds_read_b128 v[210:213], v186 offset:4672
	v_mfma_f32_16x16x32_bf16 v[92:95], v[92:95], v[4:7], 0
	s_waitcnt lgkmcnt(0)
	v_mfma_f32_16x16x32_bf16 v[92:95], v[210:213], v[8:11], v[92:95]
	ds_read_b128 v[210:213], v186 offset:6976
	v_mfma_f32_16x16x32_bf16 v[96:99], v[96:99], v[4:7], 0
	s_waitcnt lgkmcnt(0)
	v_mfma_f32_16x16x32_bf16 v[96:99], v[210:213], v[8:11], v[96:99]
	ds_read_b128 v[210:213], v186 offset:9280
	v_mfma_f32_16x16x32_bf16 v[188:191], v[188:191], v[4:7], 0
	s_waitcnt lgkmcnt(0)
	v_mfma_f32_16x16x32_bf16 v[210:213], v[210:213], v[8:11], v[188:191]
	s_nop 5
	ds_read_b128 v[188:191], v186 offset:11584
	v_mfma_f32_16x16x32_bf16 v[198:201], v[214:217], v[8:11], v[198:201]
	ds_read_b128 v[214:217], v186 offset:16192
	v_mfma_f32_16x16x32_bf16 v[192:195], v[192:195], v[4:7], 0
	v_mfma_f32_16x16x32_bf16 v[206:209], v[206:209], v[4:7], 0
	s_waitcnt lgkmcnt(1)
	v_mfma_f32_16x16x32_bf16 v[190:193], v[188:191], v[8:11], v[192:195]
	s_waitcnt lgkmcnt(0)
	v_mfma_f32_16x16x32_bf16 v[206:209], v[214:217], v[8:11], v[206:209]
	s_setprio 0
	v_max_f32_e32 v0, v87, v87
	v_max_f32_e32 v188, v86, v86
	v_max_f32_e32 v0, v188, v0
	v_max_f32_e32 v188, v91, v91
	v_max_f32_e32 v189, v90, v90
	v_max_f32_e32 v188, v189, v188
	v_max3_f32 v0, v84, v85, v0
	v_max3_f32 v188, v88, v89, v188
	v_max3_f32 v0, v0, s71, v188
	v_max_f32_e32 v188, v95, v95
	v_max_f32_e32 v189, v94, v94
	v_max_f32_e32 v188, v189, v188
	v_max_f32_e32 v189, v99, v99
	v_max_f32_e32 v194, v98, v98
	v_max_f32_e32 v189, v194, v189
	v_max3_f32 v188, v92, v93, v188
	v_max3_f32 v189, v96, v97, v189
	v_max3_f32 v0, v0, v188, v189
	v_max_f32_e32 v188, v213, v213
	v_max_f32_e32 v189, v212, v212
	v_max_f32_e32 v188, v189, v188
	v_max_f32_e32 v189, v193, v193
	v_max_f32_e32 v194, v192, v192
	v_max_f32_e32 v189, v194, v189
	v_max3_f32 v188, v210, v211, v188
	v_max3_f32 v189, v190, v191, v189
	v_max3_f32 v0, v0, v188, v189
	v_max_f32_e32 v188, v201, v201
	v_max_f32_e32 v189, v200, v200
	v_max_f32_e32 v188, v189, v188
	v_max_f32_e32 v189, v209, v209
	v_max_f32_e32 v194, v208, v208
	v_max_f32_e32 v189, v194, v189
	v_max3_f32 v188, v198, v199, v188
	v_max3_f32 v189, v206, v207, v189
	v_max3_f32 v0, v0, v188, v189
	v_mov_b32_e32 v188, v0
	s_nop 1
	v_permlane16_swap_b32_e32 v0, v188
	v_max_f32_e32 v188, v188, v188
	v_max_f32_e32 v0, v0, v0
	v_max_f32_e32 v0, v0, v188
	v_mov_b32_e32 v188, v0
	s_nop 1
	v_permlane32_swap_b32_e32 v0, v188
	v_max3_f32 v188, v3, v0, v188
	v_cmp_neq_f32_e32 vcc, s71, v188
	s_nop 1
	v_cndmask_b32_e32 v0, 0, v188, vcc
	v_sub_f32_e32 v84, v84, v0
	v_sub_f32_e32 v88, v88, v0
	v_exp_f32_e32 v84, v84
	v_exp_f32_e32 v189, v88
	v_sub_f32_e32 v85, v85, v0
	v_sub_f32_e32 v88, v89, v0
	v_exp_f32_e32 v85, v85
	v_exp_f32_e32 v194, v88
	v_sub_f32_e32 v86, v86, v0
	v_sub_f32_e32 v90, v90, v0
	v_exp_f32_e32 v86, v86
	v_exp_f32_e32 v195, v90
	v_sub_f32_e32 v87, v87, v0
	v_sub_f32_e32 v90, v91, v0
	v_exp_f32_e32 v87, v87
	v_exp_f32_e32 v204, v90
	v_add_f32_e32 v88, v189, v84
	v_add_f32_e32 v88, 0, v88
	v_add_f32_e32 v89, v194, v85
	v_add_f32_e32 v88, v89, v88
	v_add_f32_e32 v89, v195, v86
	v_add_f32_e32 v88, v89, v88
	v_add_f32_e32 v89, v204, v87
	v_add_f32_e32 v89, v89, v88
	v_sub_f32_e32 v88, v92, v0
	v_exp_f32_e32 v205, v88
	v_sub_f32_e32 v88, v96, v0
	v_exp_f32_e32 v214, v88
	v_sub_f32_e32 v88, v93, v0
	v_sub_f32_e32 v90, v97, v0
	v_exp_f32_e32 v88, v88
	v_exp_f32_e32 v90, v90
	v_add_f32_e32 v91, v214, v205
	v_cvt_pk_bf16_f32 v84, v84, v85
	v_cvt_pk_bf16_f32 v85, v86, v87
	v_pk_add_f32 v[86:87], v[90:91], v[88:89]
	v_sub_f32_e32 v3, v3, v0
	v_pk_add_f32 v[92:93], v[86:87], v[86:87] op_sel_hi:[0,1]
	v_sub_f32_e32 v86, v94, v0
	v_exp_f32_e32 v89, v86
	v_sub_f32_e32 v86, v98, v0
	v_exp_f32_e32 v91, v86
	v_sub_f32_e32 v86, v95, v0
; #define LAS __attribute__((address_space(3)))
; __device__ __forceinline__ f32x4 mfma16(bf16x8 a, bf16x8 b, f32x4 c) { return __builtin_amdgcn_mfma_f32_16x16x32_bf16(a, b, c, 0, 0, 0); }
; template <int ND> ...
;     ...
;     l_run = l_run * alpha + ps_sum; m_run = m_new;
;     __builtin_amdgcn_s_setprio(1);
; #pragma unroll
;     for (int d = 0; d < 4; ++d) { O[d] = O[d] * alpha;
; #pragma unroll
;         for (int g = 0; g < ND; ++g) {
;             const u32x2 va = *(const LAS u32x2*)(lds + vbase + (d * 16 + fr) * vstr + (key0[g] + fq * 4) * 2);
;             const u32x2 vb = *(const LAS u32x2*)(lds + vbase + (d * 16 + fr) * vstr + (key0[g] + 16 + fq * 4) * 2);
;             u32x4 vw; vw.x = va.x; vw.y = va.y; vw.z = vb.x; vw.w = vb.y;
;             O[d] = mfma16(as_bf8(vw), pf[g], O[d]); } }
	v_exp_f32_e32 v92, v86
	v_sub_f32_e32 v86, v99, v0
	v_exp_f32_e32 v94, v86
	v_add_f32_e32 v95, v91, v89
	v_cvt_pk_bf16_f32 v86, v189, v194
	v_cvt_pk_bf16_f32 v87, v195, v204
	v_pk_add_f32 v[96:97], v[94:95], v[92:93]
	v_sub_f32_e32 v93, v210, v0
	v_exp_f32_e32 v95, v93
	v_sub_f32_e32 v93, v190, v0
	v_pk_add_f32 v[96:97], v[96:97], v[96:97] op_sel_hi:[0,1]
	v_exp_f32_e32 v189, v93
	v_sub_f32_e32 v93, v211, v0
	v_exp_f32_e32 v96, v93
	v_sub_f32_e32 v93, v191, v0
	v_exp_f32_e32 v98, v93
	v_add_f32_e32 v99, v189, v95
	v_cvt_pk_bf16_f32 v88, v205, v88
	v_cvt_pk_bf16_f32 v89, v89, v92
	v_pk_add_f32 v[92:93], v[98:99], v[96:97]
	v_cvt_pk_bf16_f32 v90, v214, v90
	v_cvt_pk_bf16_f32 v91, v91, v94
	s_nop 0
	v_pk_add_f32 v[190:191], v[92:93], v[92:93] op_sel_hi:[0,1]
	v_sub_f32_e32 v92, v212, v0
	v_exp_f32_e32 v97, v92
	v_sub_f32_e32 v92, v192, v0
	v_exp_f32_e32 v99, v92
	v_sub_f32_e32 v92, v213, v0
	v_exp_f32_e32 v190, v92
	v_sub_f32_e32 v92, v193, v0
	v_exp_f32_e32 v192, v92
	v_add_f32_e32 v193, v99, v97
	v_pk_add_f32 v[92:93], v[192:193], v[190:191]
	s_nop 0
	v_pk_add_f32 v[194:195], v[92:93], v[92:93] op_sel_hi:[0,1]
	v_sub_f32_e32 v92, v198, v0
	v_exp_f32_e32 v193, v92
	v_sub_f32_e32 v92, v206, v0
	v_exp_f32_e32 v204, v92
	v_sub_f32_e32 v92, v199, v0
	v_exp_f32_e32 v194, v92
	v_sub_f32_e32 v92, v207, v0
	v_exp_f32_e32 v198, v92
	v_add_f32_e32 v199, v204, v193
	v_cvt_pk_bf16_f32 v92, v95, v96
	v_cvt_pk_bf16_f32 v93, v97, v190
	v_pk_add_f32 v[94:95], v[198:199], v[194:195]
	s_nop 0
	v_pk_add_f32 v[190:191], v[94:95], v[94:95] op_sel_hi:[0,1]
	v_sub_f32_e32 v94, v200, v0
	v_exp_f32_e32 v195, v94
	v_sub_f32_e32 v94, v208, v0
	v_exp_f32_e32 v199, v94
	v_sub_f32_e32 v94, v201, v0
	v_sub_f32_e32 v0, v209, v0
	v_exp_f32_e32 v190, v94
	v_exp_f32_e32 v200, v0
	v_exp_f32_e32 v0, v3
	v_add_f32_e32 v201, v199, v195
	v_cvt_pk_bf16_f32 v94, v189, v98
	v_pk_add_f32 v[96:97], v[200:201], v[190:191]
	v_cvt_pk_bf16_f32 v95, v99, v192
	s_nop 0
	v_add_f32_e32 v189, v96, v97
	v_fmac_f32_e32 v189, v2, v0
	v_cvt_pk_bf16_f32 v96, v193, v194
	v_cvt_pk_bf16_f32 v97, v195, v190
	v_cvt_pk_bf16_f32 v98, v204, v198
	v_cvt_pk_bf16_f32 v99, v199, v200
	s_setprio 1
	v_add_u32_e32 v219, 0x3000, v234
	ds_read2_b64 v[190:193], v219 offset0:96 offset1:100
	ds_read2_b64 v[198:201], v234 offset0:8 offset1:12
	ds_read2_b64 v[206:209], v187 offset0:8 offset1:12
	ds_read2_b64 v[210:213], v235 offset0:72 offset1:76
	ds_read2_b64 v[214:217], v219 offset0:104 offset1:108
	v_pk_mul_f32 v[68:69], v[68:69], v[0:1] op_sel_hi:[1,0]
	v_pk_mul_f32 v[70:71], v[70:71], v[0:1] op_sel_hi:[1,0]
	v_pk_mul_f32 v[80:81], v[80:81], v[0:1] op_sel_hi:[1,0]
	v_pk_mul_f32 v[82:83], v[82:83], v[0:1] op_sel_hi:[1,0]
	v_pk_mul_f32 v[72:73], v[72:73], v[0:1] op_sel_hi:[1,0]
	v_pk_mul_f32 v[74:75], v[74:75], v[0:1] op_sel_hi:[1,0]
	v_pk_mul_f32 v[76:77], v[76:77], v[0:1] op_sel_hi:[1,0]
	v_pk_mul_f32 v[78:79], v[78:79], v[0:1] op_sel_hi:[1,0]
	s_waitcnt lgkmcnt(5)
	v_mfma_f32_16x16x32_bf16 v[68:71], v[220:223], v[84:87], v[68:71]
	v_mfma_f32_16x16x32_bf16 v[80:83], v[224:227], v[84:87], v[80:83]
	v_mfma_f32_16x16x32_bf16 v[72:75], v[248:251], v[84:87], v[72:75]
	ds_read2_b64 v[220:223], v234 offset0:16 offset1:20
	ds_read2_b64 v[224:227], v187 offset0:16 offset1:20
	ds_read2_b64 v[248:251], v235 offset0:80 offset1:84
	s_waitcnt lgkmcnt(7)
	v_mfma_f32_16x16x32_bf16 v[76:79], v[190:193], v[84:87], v[76:79]
	ds_read2_b64 v[190:193], v219 offset0:112 offset1:116
	s_waitcnt lgkmcnt(7)
	v_mfma_f32_16x16x32_bf16 v[68:71], v[198:201], v[88:91], v[68:71]
	ds_read2_b64 v[198:201], v234 offset0:24 offset1:28
	s_waitcnt lgkmcnt(7)
	v_mfma_f32_16x16x32_bf16 v[80:83], v[206:209], v[88:91], v[80:83]
	ds_read2_b64 v[206:209], v187 offset0:24 offset1:28
	s_waitcnt lgkmcnt(7)
	v_mfma_f32_16x16x32_bf16 v[72:75], v[210:213], v[88:91], v[72:75]
	ds_read2_b64 v[210:213], v235 offset0:88 offset1:92
	s_waitcnt lgkmcnt(7)
	v_mfma_f32_16x16x32_bf16 v[76:79], v[214:217], v[88:91], v[76:79]
	ds_read2_b64 v[214:217], v219 offset0:120 offset1:124
	s_waitcnt lgkmcnt(7)
	v_mfma_f32_16x16x32_bf16 v[68:71], v[220:223], v[92:95], v[68:71]
	s_waitcnt lgkmcnt(6)
	v_mfma_f32_16x16x32_bf16 v[80:83], v[224:227], v[92:95], v[80:83]
	s_waitcnt lgkmcnt(5)
	v_mfma_f32_16x16x32_bf16 v[72:75], v[248:251], v[92:95], v[72:75]
	s_waitcnt lgkmcnt(4)
	v_mfma_f32_16x16x32_bf16 v[76:79], v[190:193], v[92:95], v[76:79]
	s_waitcnt lgkmcnt(3)
	v_mfma_f32_16x16x32_bf16 v[68:71], v[198:201], v[96:99], v[68:71]
	s_waitcnt lgkmcnt(2)
	v_mfma_f32_16x16x32_bf16 v[80:83], v[206:209], v[96:99], v[80:83]
	s_waitcnt lgkmcnt(1)
	v_mfma_f32_16x16x32_bf16 v[72:75], v[210:213], v[96:99], v[72:75]
	s_waitcnt lgkmcnt(0)
	v_mfma_f32_16x16x32_bf16 v[76:79], v[214:217], v[96:99], v[76:79]
	s_setprio 0
	s_mov_b32 s3, 5
	s_mov_b64 s[88:89], 0
	s_andn2_b64 vcc, exec, s[50:51]
	s_mov_b64 s[72:73], -1
	s_cbranch_vccz .LBB0_665

; #define LAS __attribute__((address_space(3)))
; __device__ __forceinline__ f32x4 mfma16(bf16x8 a, bf16x8 b, f32x4 c) { return __builtin_amdgcn_mfma_f32_16x16x32_bf16(a, b, c, 0, 0, 0); }
; template <int ND> ...
;     ...
;     __builtin_amdgcn_s_setprio(1);
; #pragma unroll
;     for (int kk = 0; kk < 2; ++kk)
; #pragma unroll
;         for (int u = 0; u < 2 * ND; ++u) {
;             const bf16x8 kf = *(const LAS bf16x8*)(lds + kbase + (key0[u >> 1] + (u & 1) * 16 + fr) * 144 + kk * 64 + fq * 16);
;             sc[u] = mfma16(kf, qf[kk], sc[u]); }
;     __builtin_amdgcn_s_setprio(0);
;     if (loc) {
; #pragma unroll
;         for (int g = 0; g < ND; ++g)
; #pragma unroll
;             for (int i = 0; i < 4; ++i) {
;                 const int ck0 = cst + fq * 4 + i, ck1 = ck0 + 16;
;                 const int rel0 = min(max(ck0 - cq + 15, 0), 30), rel1 = min(max(ck1 - cq + 15, 0), 30);
;                 const bool v0 = (ck0 >= c0w) && (ck0 < c0w + 16), v1 = (ck1 >= c0w) && (ck1 < c0w + 16);
;                 sc[2 * g][i] = v0 ? sc[2 * g][i] + rpb[dr[g] * 31 + rel0] : -INFINITY;
;                 sc[2 * g + 1][i] = v1 ? sc[2 * g + 1][i] + rpb[dr[g] * 31 + rel1] : -INFINITY; }
.LBB0_775:
	v_add_u32_e32 v219, 0x1e764, v192
	v_add_u32_e32 v220, 0x1e764, v193
	v_add_u32_e32 v221, 0x1e764, v194
	v_add_u32_e32 v222, 0x1e764, v195
	v_add_u32_e32 v223, 0x1e764, v206
	v_add_u32_e32 v224, 0x1e764, v207
	v_add_u32_e32 v225, 0x1e764, v208
	v_add_u32_e32 v226, 0x1e764, v209
	ds_read_b32 v227, v219
	ds_read_b32 v219, v219 offset:124
	ds_read_b32 v234, v220
	ds_read_b32 v220, v220 offset:124
	ds_read_b32 v235, v221
	ds_read_b32 v221, v221 offset:124
	ds_read_b32 v248, v222
	ds_read_b32 v222, v222 offset:124
	ds_read_b32 v249, v223
	ds_read_b32 v223, v223 offset:124
	ds_read_b32 v250, v224
	ds_read_b32 v224, v224 offset:124
	s_setprio 1
	v_add_u32_e32 v2, v166, v191
	ds_read_b128 v[92:95], v2 offset:6912
	v_add_u32_e32 v0, v175, v210
	ds_read_b128 v[84:87], v0
	ds_read_b128 v[88:91], v2
	s_waitcnt lgkmcnt(2)
	ds_read_b32 v251, v225
	ds_read_b32 v225, v225 offset:124
	ds_read_b32 v3, v226
	ds_read_b32 v226, v226 offset:124
	v_mfma_f32_16x16x32_bf16 v[198:201], v[92:95], v[4:7], 0
	ds_read_b128 v[92:95], v2 offset:9216
	s_waitcnt lgkmcnt(0)
	v_mfma_f32_16x16x32_bf16 v[212:215], v[92:95], v[4:7], 0
	ds_read_b128 v[92:95], v0 offset:64
	v_mfma_f32_16x16x32_bf16 v[84:87], v[84:87], v[4:7], 0
	s_waitcnt lgkmcnt(0)
	v_mfma_f32_16x16x32_bf16 v[96:99], v[92:95], v[8:11], v[84:87]
	s_nop 5
	ds_read_b128 v[84:87], v2 offset:64
	v_mfma_f32_16x16x32_bf16 v[88:91], v[88:91], v[4:7], 0
	s_waitcnt lgkmcnt(0)
	v_mfma_f32_16x16x32_bf16 v[92:95], v[84:87], v[8:11], v[88:91]
	ds_read_b128 v[84:87], v2 offset:6976
	s_nop 4
	ds_read_b128 v[88:91], v2 offset:9280
	s_waitcnt lgkmcnt(1)
	v_mfma_f32_16x16x32_bf16 v[84:87], v[84:87], v[8:11], v[198:201]
	s_waitcnt lgkmcnt(0)
	v_mfma_f32_16x16x32_bf16 v[88:91], v[88:91], v[8:11], v[212:215]
	s_setprio 0
	v_mov_b32_e32 v216, 0xff800000
	s_waitcnt lgkmcnt(0)
; #define LAS __attribute__((address_space(3)))
; __device__ __forceinline__ unsigned pk_bf16(float lo, float hi) { unsigned r; asm volatile("v_cvt_pk_bf16_f32 %0, %1, %2" : "=v"(r) : "v"(lo), "v"(hi)); return r; }
; template <int ND> ...
;     ...
;     if (loc) {
; #pragma unroll
;         for (int g = 0; g < ND; ++g)
; #pragma unroll
;             for (int i = 0; i < 4; ++i) {
;                 const int ck0 = cst + fq * 4 + i, ck1 = ck0 + 16;
;                 const int rel0 = min(max(ck0 - cq + 15, 0), 30), rel1 = min(max(ck1 - cq + 15, 0), 30);
;                 const bool v0 = (ck0 >= c0w) && (ck0 < c0w + 16), v1 = (ck1 >= c0w) && (ck1 < c0w + 16);
;                 sc[2 * g][i] = v0 ? sc[2 * g][i] + rpb[dr[g] * 31 + rel0] : -INFINITY;
;                 sc[2 * g + 1][i] = v1 ? sc[2 * g + 1][i] + rpb[dr[g] * 31 + rel1] : -INFINITY; }
;     }
;     float mx = -INFINITY;
; #pragma unroll
;     for (int u = 0; u < 2 * ND; ++u) mx = fmaxf(mx, fmaxf(fmaxf(sc[u][0], sc[u][1]), fmaxf(sc[u][2], sc[u][3])));
;     mx = xmax16(mx); mx = xmax32(mx);
;     const float m_new = fmaxf(m_run, mx);
;     const float m_use = (m_new == -INFINITY) ? 0.f : m_new;
;     const float alpha = __builtin_amdgcn_exp2f(m_run - m_use);
;     float ps_sum = 0.f; bf16x8 pf[ND];
; #pragma unroll
;     for (int g = 0; g < ND; ++g) { float pv[8];
; #pragma unroll
;         for (int i = 0; i < 4; ++i) { pv[i] = __builtin_amdgcn_exp2f(sc[2 * g][i] - m_use); pv[4 + i] = __builtin_amdgcn_exp2f(sc[2 * g + 1][i] - m_use); ps_sum += pv[i] + pv[4 + i]; }
;         u32x4 pw; pw.x = pk_bf16(pv[0], pv[1]); pw.y = pk_bf16(pv[2], pv[3]); pw.z = pk_bf16(pv[4], pv[5]); pw.w = pk_bf16(pv[6], pv[7]);
;         pf[g] = as_bf8(pw); }
;     l_run = l_run * alpha + ps_sum; m_run = m_new;
;     __builtin_amdgcn_s_setprio(1);
; #pragma unroll
;     for (int d = 0; d < 4; ++d) { O[d] = O[d] * alpha;
; #pragma unroll
;         for (int g = 0; g < ND; ++g) {
;             const u32x2 va = *(const LAS u32x2*)(lds + vbase + (d * 16 + fr) * vstr + (key0[g] + fq * 4) * 2);
;             const u32x2 vb = *(const LAS u32x2*)(lds + vbase + (d * 16 + fr) * vstr + (key0[g] + 16 + fq * 4) * 2);
;             u32x4 vw; vw.x = va.x; vw.y = va.y; vw.z = vb.x; vw.w = vb.y;
;             O[d] = mfma16(as_bf8(vw), pf[g], O[d]); } }
	v_add_f32_e32 v227, v96, v227
	v_cndmask_b32_e64 v2, v216, v227, s[64:65]
	v_add_f32_e32 v234, v92, v234
	v_cndmask_b32_e64 v0, v216, v234, s[90:91]
	v_add_f32_e32 v235, v97, v235
	v_cndmask_b32_e64 v96, v216, v235, s[74:75]
	v_add_f32_e32 v248, v93, v248
	v_cndmask_b32_e64 v92, v216, v248, s[96:97]
	v_add_f32_e32 v249, v98, v249
	v_cndmask_b32_e64 v97, v216, v249, s[8:9]
	v_add_f32_e32 v250, v94, v250
	v_cndmask_b32_e64 v93, v216, v250, s[86:87]
	v_add_f32_e32 v251, v99, v251
	v_cndmask_b32_e64 v98, v216, v251, s[60:61]
	v_add_f32_e32 v3, v95, v3
	v_cndmask_b32_e64 v94, v216, v3, s[52:53]
	v_add_f32_e32 v219, v84, v219
	v_cndmask_b32_e64 v99, v216, v219, s[64:65]
	v_add_f32_e32 v220, v88, v220
	v_cndmask_b32_e64 v95, v216, v220, s[90:91]
	v_add_f32_e32 v221, v85, v221
	v_cndmask_b32_e64 v88, v216, v221, s[74:75]
	v_add_f32_e32 v222, v89, v222
	v_cndmask_b32_e64 v84, v216, v222, s[96:97]
	v_add_f32_e32 v223, v86, v223
	v_cndmask_b32_e64 v212, v216, v223, s[8:9]
	v_add_f32_e32 v224, v90, v224
	v_cndmask_b32_e64 v85, v216, v224, s[86:87]
	v_add_f32_e32 v225, v87, v225
	v_cndmask_b32_e64 v90, v216, v225, s[60:61]
	v_add_f32_e32 v226, v91, v226
	v_cndmask_b32_e64 v86, v216, v226, s[52:53]
	v_add_u32_e32 v219, 0xb000, v190
	v_add_u32_e32 v234, 0xd800, v190
	v_add_u32_e32 v235, 0x10600, v190
	ds_read2_b64 v[220:223], v219 offset0:128 offset1:132
	ds_read2_b64 v[224:227], v234 offset0:160 offset1:164
	ds_read2_b64 v[248:251], v235 offset1:4
	v_max_f32_e32 v3, v98, v98
	v_max_f32_e32 v87, v97, v97
	v_max_f32_e32 v3, v87, v3
	v_max_f32_e32 v87, v94, v94
	v_max_f32_e32 v89, v93, v93
	v_max_f32_e32 v87, v89, v87
	v_max3_f32 v3, v2, v96, v3
	v_max3_f32 v87, v0, v92, v87
	v_max3_f32 v3, v3, s71, v87
	v_max_f32_e32 v87, v90, v90
	v_max_f32_e32 v89, v212, v212
	v_max_f32_e32 v87, v89, v87
	v_max_f32_e32 v89, v86, v86
	v_max_f32_e32 v91, v85, v85
	v_max_f32_e32 v89, v91, v89
	v_max3_f32 v87, v99, v88, v87
	v_max3_f32 v89, v95, v84, v89
	v_max3_f32 v3, v3, v87, v89
	v_mov_b32_e32 v87, v3
	s_nop 1
	v_permlane16_swap_b32_e32 v3, v87
	v_max_f32_e32 v87, v87, v87
	v_max_f32_e32 v3, v3, v3
	v_max_f32_e32 v3, v3, v87
	v_mov_b32_e32 v87, v3
	s_nop 1
	v_permlane32_swap_b32_e32 v3, v87
	v_max3_f32 v3, v188, v3, v87
	v_cmp_neq_f32_e32 vcc, s71, v3
	s_nop 1
	v_cndmask_b32_e32 v87, 0, v3, vcc
	v_sub_f32_e32 v2, v2, v87
	v_sub_f32_e32 v0, v0, v87
	v_exp_f32_e32 v2, v2
	v_exp_f32_e32 v91, v0
	v_sub_f32_e32 v0, v96, v87
	v_sub_f32_e32 v89, v92, v87
	v_exp_f32_e32 v0, v0
	v_exp_f32_e32 v198, v89
	v_add_f32_e32 v199, v91, v2
	v_sub_f32_e32 v92, v93, v87
	v_sub_f32_e32 v89, v97, v87
	v_pk_add_f32 v[200:201], v[198:199], v[0:1]
	v_exp_f32_e32 v199, v92
	v_pk_add_f32 v[200:201], v[200:201], v[200:201] op_sel_hi:[0,1]
	v_sub_f32_e32 v92, v98, v87
	v_exp_f32_e32 v89, v89
	v_exp_f32_e32 v200, v92
	v_sub_f32_e32 v92, v94, v87
	v_exp_f32_e32 v92, v92
	v_add_f32_e32 v93, v199, v89
	v_sub_f32_e32 v94, v95, v87
	v_exp_f32_e32 v204, v94
	v_pk_add_f32 v[96:97], v[92:93], v[200:201]
	v_sub_f32_e32 v93, v99, v87
	v_pk_add_f32 v[96:97], v[96:97], v[96:97] op_sel_hi:[0,1]
	v_exp_f32_e32 v93, v93
	v_sub_f32_e32 v88, v88, v87
	v_sub_f32_e32 v84, v84, v87
	v_exp_f32_e32 v96, v88
	v_exp_f32_e32 v94, v84
	v_cvt_pk_bf16_f32 v88, v2, v0
	v_add_f32_e32 v95, v204, v93
	v_sub_f32_e32 v0, v212, v87
	v_pk_add_f32 v[98:99], v[94:95], v[96:97]
	v_exp_f32_e32 v95, v0
	v_sub_f32_e32 v0, v85, v87
	v_pk_add_f32 v[98:99], v[98:99], v[98:99] op_sel_hi:[0,1]
	v_exp_f32_e32 v97, v0
	v_sub_f32_e32 v0, v90, v87
	v_exp_f32_e32 v98, v0
	v_sub_f32_e32 v0, v86, v87
	v_cvt_pk_bf16_f32 v89, v89, v200
	v_exp_f32_e32 v200, v0
	v_sub_f32_e32 v188, v188, v87
	v_exp_f32_e32 v0, v188
	v_add_f32_e32 v201, v97, v95
	v_pk_add_f32 v[84:85], v[200:201], v[98:99]
	v_cvt_pk_bf16_f32 v90, v91, v198
	v_cvt_pk_bf16_f32 v91, v199, v92
	s_nop 0
	v_add_f32_e32 v2, v84, v85
	v_fmac_f32_e32 v2, v189, v0
	v_cvt_pk_bf16_f32 v84, v93, v96
	v_cvt_pk_bf16_f32 v85, v95, v98
	v_cvt_pk_bf16_f32 v86, v204, v94
	v_cvt_pk_bf16_f32 v87, v97, v200
	s_setprio 1
	v_add_u32_e32 v216, 0x12f00, v190
	ds_read2_b64 v[92:95], v216 offset1:4
	ds_read2_b64 v[96:99], v219 offset0:144 offset1:148
	ds_read2_b64 v[198:201], v234 offset0:176 offset1:180
	ds_read2_b64 v[212:215], v235 offset0:16 offset1:20
	v_pk_mul_f32 v[68:69], v[68:69], v[0:1] op_sel_hi:[1,0]
	v_pk_mul_f32 v[70:71], v[70:71], v[0:1] op_sel_hi:[1,0]
	v_pk_mul_f32 v[80:81], v[80:81], v[0:1] op_sel_hi:[1,0]
	v_pk_mul_f32 v[82:83], v[82:83], v[0:1] op_sel_hi:[1,0]
	v_pk_mul_f32 v[72:73], v[72:73], v[0:1] op_sel_hi:[1,0]
	v_pk_mul_f32 v[74:75], v[74:75], v[0:1] op_sel_hi:[1,0]
	v_pk_mul_f32 v[76:77], v[76:77], v[0:1] op_sel_hi:[1,0]
	v_pk_mul_f32 v[78:79], v[78:79], v[0:1] op_sel_hi:[1,0]
	s_waitcnt lgkmcnt(4)
	v_mfma_f32_16x16x32_bf16 v[68:71], v[220:223], v[88:91], v[68:71]
	v_mfma_f32_16x16x32_bf16 v[80:83], v[224:227], v[88:91], v[80:83]
	v_mfma_f32_16x16x32_bf16 v[72:75], v[248:251], v[88:91], v[72:75]
	ds_read2_b64 v[220:223], v216 offset0:16 offset1:20
	s_waitcnt lgkmcnt(4)
	v_mfma_f32_16x16x32_bf16 v[76:79], v[92:95], v[88:91], v[76:79]
	s_waitcnt lgkmcnt(3)
	v_mfma_f32_16x16x32_bf16 v[68:71], v[96:99], v[84:87], v[68:71]
	s_waitcnt lgkmcnt(2)
	v_mfma_f32_16x16x32_bf16 v[80:83], v[198:201], v[84:87], v[80:83]
	s_waitcnt lgkmcnt(1)
	v_mfma_f32_16x16x32_bf16 v[72:75], v[212:215], v[84:87], v[72:75]
	s_waitcnt lgkmcnt(0)
	v_mfma_f32_16x16x32_bf16 v[76:79], v[220:223], v[84:87], v[76:79]
	s_setprio 0
	s_add_i32 s47, s47, 2
	v_add_u32_e32 v190, 0x100, v190
	v_add_u32_e32 v191, 0x4800, v191
	v_add_u32_e32 v192, 0xf8, v192
	v_add_u32_e32 v193, 0xf8, v193
	v_add_u32_e32 v194, 0xf8, v194
	v_add_u32_e32 v195, 0xf8, v195
	v_add_u32_e32 v206, 0xf8, v206
	v_add_u32_e32 v207, 0xf8, v207
	v_add_u32_e32 v208, 0xf8, v208
	v_add_u32_e32 v209, 0xf8, v209
	v_add_u32_e32 v210, 0x4800, v210
	s_cmp_lt_i32 s47, s46
	v_add_u32_e32 v211, 0x100, v211
	s_cbranch_scc0 .LBB0_810
	v_mov_b32_e32 v188, v3
	v_mov_b32_e32 v189, v2
	s_branch .LBB0_775

; #define LAS __attribute__((address_space(3)))
; __device__ __forceinline__ unsigned pk_bf16(float lo, float hi) { unsigned r; asm volatile("v_cvt_pk_bf16_f32 %0, %1, %2" : "=v"(r) : "v"(lo), "v"(hi)); return r; }
; template <int ND> ...
;     ...
;     if (loc) {
; #pragma unroll
;         for (int g = 0; g < ND; ++g)
; #pragma unroll
;             for (int i = 0; i < 4; ++i) {
;                 const int ck0 = cst + fq * 4 + i, ck1 = ck0 + 16;
;                 const int rel0 = min(max(ck0 - cq + 15, 0), 30), rel1 = min(max(ck1 - cq + 15, 0), 30);
;                 const bool v0 = (ck0 >= c0w) && (ck0 < c0w + 16), v1 = (ck1 >= c0w) && (ck1 < c0w + 16);
;                 sc[2 * g][i] = v0 ? sc[2 * g][i] + rpb[dr[g] * 31 + rel0] : -INFINITY;
;                 sc[2 * g + 1][i] = v1 ? sc[2 * g + 1][i] + rpb[dr[g] * 31 + rel1] : -INFINITY; }
;     }
;     float mx = -INFINITY;
; #pragma unroll
;     for (int u = 0; u < 2 * ND; ++u) mx = fmaxf(mx, fmaxf(fmaxf(sc[u][0], sc[u][1]), fmaxf(sc[u][2], sc[u][3])));
;     mx = xmax16(mx); mx = xmax32(mx);
;     const float m_new = fmaxf(m_run, mx);
;     const float m_use = (m_new == -INFINITY) ? 0.f : m_new;
;     const float alpha = __builtin_amdgcn_exp2f(m_run - m_use);
;     float ps_sum = 0.f; bf16x8 pf[ND];
; #pragma unroll
;     for (int g = 0; g < ND; ++g) { float pv[8];
; #pragma unroll
;         for (int i = 0; i < 4; ++i) { pv[i] = __builtin_amdgcn_exp2f(sc[2 * g][i] - m_use); pv[4 + i] = __builtin_amdgcn_exp2f(sc[2 * g + 1][i] - m_use); ps_sum += pv[i] + pv[4 + i]; }
;         u32x4 pw; pw.x = pk_bf16(pv[0], pv[1]); pw.y = pk_bf16(pv[2], pv[3]); pw.z = pk_bf16(pv[4], pv[5]); pw.w = pk_bf16(pv[6], pv[7]);
;         pf[g] = as_bf8(pw); }
;     l_run = l_run * alpha + ps_sum; m_run = m_new;
;     __builtin_amdgcn_s_setprio(1);
; #pragma unroll
;     for (int d = 0; d < 4; ++d) { O[d] = O[d] * alpha;
; #pragma unroll
;         for (int g = 0; g < ND; ++g) {
;             const u32x2 va = *(const LAS u32x2*)(lds + vbase + (d * 16 + fr) * vstr + (key0[g] + fq * 4) * 2);
;             const u32x2 vb = *(const LAS u32x2*)(lds + vbase + (d * 16 + fr) * vstr + (key0[g] + 16 + fq * 4) * 2);
;             u32x4 vw; vw.x = va.x; vw.y = va.y; vw.z = vb.x; vw.w = vb.y;
;             O[d] = mfma16(as_bf8(vw), pf[g], O[d]); } }
.LBB0_811:
	s_sub_i32 s3, s4, s3
	s_lshl_b32 s3, s3, 6
	s_or_b32 s3, s3, s56
	s_add_i32 s46, s82, s4
	s_mulk_i32 s46, 0x7c
	s_add_i32 s46, s46, 0
	s_add_i32 s46, s46, 0x1e400
	v_lshl_add_u32 v219, v147, 2, s46
	v_lshl_add_u32 v220, v146, 2, s46
	v_lshl_add_u32 v221, v149, 2, s46
	v_lshl_add_u32 v222, v148, 2, s46
	v_lshl_add_u32 v223, v151, 2, s46
	v_lshl_add_u32 v224, v150, 2, s46
	v_lshl_add_u32 v225, v153, 2, s46
	v_lshl_add_u32 v226, v152, 2, s46
	ds_read_b32 v219, v219 offset:868
	ds_read_b32 v220, v220 offset:868
	ds_read_b32 v221, v221 offset:868
	ds_read_b32 v222, v222 offset:868
	ds_read_b32 v223, v223 offset:868
	ds_read_b32 v224, v224 offset:868
	ds_read_b32 v225, v225 offset:868
	ds_read_b32 v226, v226 offset:868
	s_setprio 1
	v_add_u32_e32 v0, s3, v107
	v_mad_u64_u32 v[96:97], s[4:5], v0, s55, v[108:109]
	ds_read_b128 v[84:87], v96
	ds_read_b128 v[92:95], v96 offset:64
	ds_read_b128 v[88:91], v96 offset:2304
	s_waitcnt lgkmcnt(2)
	v_mfma_f32_16x16x32_bf16 v[84:87], v[84:87], v[4:7], 0
	s_waitcnt lgkmcnt(1)
	v_mfma_f32_16x16x32_bf16 v[84:87], v[92:95], v[8:11], v[84:87]
	ds_read_b128 v[92:95], v96 offset:2368
	s_waitcnt lgkmcnt(1)
	v_mfma_f32_16x16x32_bf16 v[88:91], v[88:91], v[4:7], 0
	s_waitcnt lgkmcnt(0)
	v_mfma_f32_16x16x32_bf16 v[88:91], v[92:95], v[8:11], v[88:91]
	s_setprio 0
	v_mov_b32_e32 v227, 0xff800000
	s_waitcnt lgkmcnt(0)
	s_nop 4
	v_add_f32_e32 v219, v84, v219
	v_cndmask_b32_e64 v92, v227, v219, s[64:65]
	v_add_f32_e32 v220, v88, v220
	v_cndmask_b32_e64 v0, v227, v220, s[90:91]
	v_add_f32_e32 v221, v85, v221
	v_cndmask_b32_e64 v88, v227, v221, s[74:75]
	v_add_f32_e32 v222, v89, v222
	v_cndmask_b32_e64 v84, v227, v222, s[96:97]
	v_add_f32_e32 v223, v86, v223
	v_cndmask_b32_e64 v89, v227, v223, s[8:9]
	v_add_f32_e32 v224, v90, v224
	v_cndmask_b32_e64 v85, v227, v224, s[86:87]
	v_add_f32_e32 v225, v87, v225
	v_cndmask_b32_e64 v90, v227, v225, s[60:61]
	v_add_f32_e32 v226, v91, v226
	v_cndmask_b32_e64 v86, v227, v226, s[52:53]
	v_add_lshl_u32 v234, s3, v106, 1
	v_add_u32_e32 v235, v157, v234
	v_add_u32_e32 v234, v156, v234
	ds_read_b64 v[220:221], v234 offset:46080
	ds_read_b64 v[222:223], v234 offset:46112
	ds_read_b64 v[224:225], v234 offset:56576
	ds_read_b64 v[226:227], v234 offset:56608
	ds_read_b64 v[248:249], v235 offset:20992
	ds_read_b64 v[250:251], v235 offset:21024
	v_max_f32_e32 v87, v90, v90
	v_max_f32_e32 v91, v89, v89
	v_max_f32_e32 v87, v91, v87
	v_max_f32_e32 v91, v86, v86
	v_max_f32_e32 v93, v85, v85
	v_max_f32_e32 v91, v93, v91
	v_max3_f32 v87, v92, v88, v87
	v_max3_f32 v91, v0, v84, v91
	v_max3_f32 v87, v87, s71, v91
	v_mov_b32_e32 v91, v87
	s_nop 1
	v_permlane16_swap_b32_e32 v87, v91
	v_max_f32_e32 v91, v91, v91
	v_max_f32_e32 v87, v87, v87
	v_max_f32_e32 v87, v87, v91
	v_mov_b32_e32 v91, v87
	s_nop 1
	v_permlane32_swap_b32_e32 v87, v91
	v_max3_f32 v97, v3, v87, v91
	v_cmp_neq_f32_e32 vcc, s71, v97
	s_nop 1
	v_cndmask_b32_e32 v87, 0, v97, vcc
	v_sub_f32_e32 v91, v92, v87
	v_sub_f32_e32 v0, v0, v87
	v_exp_f32_e32 v91, v91
	v_exp_f32_e32 v98, v0
	v_sub_f32_e32 v0, v88, v87
	v_sub_f32_e32 v84, v84, v87
	v_exp_f32_e32 v0, v0
	v_exp_f32_e32 v92, v84
	v_add_f32_e32 v93, v98, v91
	v_sub_f32_e32 v84, v89, v87
	v_sub_f32_e32 v3, v3, v87
	v_pk_add_f32 v[94:95], v[92:93], v[0:1]
	v_exp_f32_e32 v93, v84
	v_sub_f32_e32 v84, v85, v87
	v_pk_add_f32 v[94:95], v[94:95], v[94:95] op_sel_hi:[0,1]
	v_exp_f32_e32 v99, v84
	v_sub_f32_e32 v84, v90, v87
	v_exp_f32_e32 v94, v84
	v_sub_f32_e32 v84, v86, v87
	v_exp_f32_e32 v88, v84
	v_exp_f32_e32 v96, v3
	v_add_f32_e32 v89, v99, v93
	v_pk_add_f32 v[84:85], v[88:89], v[94:95]
	s_nop 0
	v_add_f32_e32 v95, v84, v85
	v_cvt_pk_bf16_f32 v84, v91, v0
	v_cvt_pk_bf16_f32 v85, v93, v94
	v_cvt_pk_bf16_f32 v86, v98, v92
	v_cvt_pk_bf16_f32 v87, v99, v88
	v_fmac_f32_e32 v95, v2, v96
	s_setprio 1
	ds_read_b64 v[88:89], v235 offset:31488
	ds_read_b64 v[90:91], v235 offset:31520
	v_pk_mul_f32 v[68:69], v[68:69], v[96:97] op_sel_hi:[1,0]
	v_pk_mul_f32 v[70:71], v[70:71], v[96:97] op_sel_hi:[1,0]
	v_pk_mul_f32 v[80:81], v[80:81], v[96:97] op_sel_hi:[1,0]
	v_pk_mul_f32 v[82:83], v[82:83], v[96:97] op_sel_hi:[1,0]
	v_pk_mul_f32 v[72:73], v[72:73], v[96:97] op_sel_hi:[1,0]
	v_pk_mul_f32 v[74:75], v[74:75], v[96:97] op_sel_hi:[1,0]
	v_pk_mul_f32 v[76:77], v[76:77], v[96:97] op_sel_hi:[1,0]
	v_pk_mul_f32 v[78:79], v[78:79], v[96:97] op_sel_hi:[1,0]
	s_waitcnt lgkmcnt(2)
	v_mfma_f32_16x16x32_bf16 v[68:71], v[220:223], v[84:87], v[68:71]
	v_mfma_f32_16x16x32_bf16 v[80:83], v[224:227], v[84:87], v[80:83]
	v_mfma_f32_16x16x32_bf16 v[72:75], v[248:251], v[84:87], v[72:75]
	s_waitcnt lgkmcnt(0)
	v_mfma_f32_16x16x32_bf16 v[76:79], v[88:91], v[84:87], v[76:79]
	s_setprio 0
	v_mov_b32_e32 v3, v97
	v_mov_b32_e32 v2, v95
	s_branch .LBB0_737
